# P0: plain weight transposes software-pipelined across items (next item's 32 loads in flight), rmsnorm loop pipelined
# speedup vs baseline: 1.0134x; 1.0016x over previous
; #define INP(i) ((const float*)(const GAS float*)KARG(8 * (i)))
; __global__ void __launch_bounds__(512, 2) fwd(Params P) {
;     ...
;         for (int it = gw; it < NITEMS; it += NGW) {
;             int r = it;
;             if (r < I0) { tr_item<1>(INP(4), 2048, 8256, nullptr, wb + OFF_WIN, scr, r, NIN / 32, lane); continue; } r -= I0;
;             if (r < I1) { tr_item<2>(INP(7), 512, 1536, INP(5), wb + OFF_WQ, scr, r, 1536 / 32, lane); continue; } r -= I1;
;             if (r < I2) { tr_item<0>(INP(8), 512, 2048, INP(6), wb + OFF_WKV, scr, r, 2048 / 32, lane); continue; } r -= I2;
;             if (r < I3) { tr_item<0>(INP(9), 1024, 2048, nullptr, wb + OFF_WSBO, scr, r, 2048 / 32, lane); continue; } r -= I3;
;             if (r < I4) { tr_item<0>(INP(10), 1024, 2048, nullptr, wb + OFF_WMLAO, scr, r, 2048 / 32, lane); continue; } r -= I4;
;             if (r < I5) { tr_item<0>(INP(11), 2048, 2048, nullptr, wb + OFF_WOUT, scr, r, 2048 / 32, lane); continue; } r -= I5;
;             if (r < I6) { tr_item<0>(INP(14), 2048, 8192, nullptr, wb + OFF_WUP, scr, r, 8192 / 32, lane); continue; } r -= I6;
;             if (r < I7) { tr_item<0>(INP(15), 8192, 2048, nullptr, wb + OFF_WDOWN, scr, r, 2048 / 32, lane); continue; } r -= I7;
;             if (r < I8) { tr_item<0>(INP(17), 256, 2048, nullptr, wb + OFF_WPLE, scr, r, 2048 / 32, lane); continue; } r -= I8;
;             tr_item<0>(INP(19), 2048, 2048, nullptr, wb + OFF_WPG, scr, r, 2048 / 32, lane);
.LBB0_24:
	s_cmpk_gt_u32 s50, 0x247f
	s_cbranch_scc1 .Lp0g_entry
	s_cmpk_gt_i32 s50, 0x20ff
	s_mov_b64 s[4:5], -1
	s_cbranch_scc0 .LBB0_126
	s_cmpk_gt_u32 s50, 0x227f
	s_cbranch_scc0 .LBB0_87
	s_and_b32 s30, s50, 0x3fc0
	v_or_b32_e32 v40, s30, v0
	s_cmpk_gt_u32 s50, 0x247f
	s_cbranch_scc0 .LBB0_66
	s_cmpk_gt_u32 s50, 0x287f
	s_cbranch_scc0 .LBB0_61
	s_cmpk_gt_u32 s50, 0x2c7f
	s_cbranch_scc0 .LBB0_56
	s_cmpk_gt_u32 s50, 0x347f
	s_cbranch_scc0 .LBB0_51
	s_cmpk_gt_u32 s50, 0x547f
	s_cbranch_scc0 .LBB0_46
	s_lshr_b32 s7, s50, 6
	s_and_b32 s4, s7, 0x1ff
	v_lshl_or_b32 v12, s4, 6, v0
	s_cmpk_gt_u32 s50, 0x747f
	s_mov_b64 s[4:5], -1
	s_cbranch_scc0 .LBB0_41
	s_lshl_b32 s4, s50, 5
	s_and_b32 s6, s4, 0x7e0
	v_or_b32_e32 v2, s6, v24
	s_cmpk_gt_u32 s50, 0x757f
	s_mov_b64 s[4:5], -1
	v_lshlrev_b32_e32 v8, 2, v2
	s_cbranch_scc0 .LBB0_36
	s_and_b32 s4, s7, 0x1ffffff
	v_lshl_or_b32 v7, s4, 6, v0
	s_mov_b64 s[4:5], s[0:1]
	s_load_dwordx2 s[34:35], s[4:5], 0x98
	s_mov_b64 s[4:5], s[0:1]
	s_load_dwordx2 s[4:5], s[4:5], 0xa8
	v_mov_b32_e32 v9, v3
	s_waitcnt lgkmcnt(0)
	v_lshl_add_u64 v[10:11], s[34:35], 0, v[8:9]
	s_mov_b32 s7, 0
	v_mov_b32_e32 v9, v31

; #define LAS __attribute__((address_space(3)))
; template <int KIND> __device__ __forceinline__ void tr_item(const float* __restrict__ W, int K, int Nsrc, const float* __restrict__ gk, bf16_t* WT, LAS float* scr, int item, int nblk, int lane) {
;     const int kb = item / nblk, nb = item - kb * nblk, k0 = 64 * kb, n0 = 32 * nb;
;     const int src = srcmap<KIND>(n0 + (lane & 31));
; #pragma unroll 8
;     for (int i = 0; i < 32; ++i) { const int kk = 2 * i + (lane >> 5); float v = 0.f; if (src >= 0) v = __builtin_nontemporal_load(&W[(size_t)(k0 + kk) * Nsrc + src]); if (gk) v *= gk[k0 + kk]; scr[kk * 33 + (lane & 31)] = v; }
;     asm volatile("s_waitcnt lgkmcnt(0)" ::: "memory");
;     const int c = lane & 7;
; #pragma unroll
;     for (int j = 0; j < 4; ++j) { const int n = (lane >> 3) + 8 * j; const LAS float* s = scr + (8 * c) * 33 + n;
;         u32x4 o; o.x = pk2(s[0 * 33], s[1 * 33]); o.y = pk2(s[2 * 33], s[3 * 33]); o.z = pk2(s[4 * 33], s[5 * 33]); o.w = pk2(s[6 * 33], s[7 * 33]);
;         *(u32x4*)(WT + (size_t)(n0 + n) * K + k0 + 8 * c) = o; }
;     asm volatile("s_waitcnt lgkmcnt(0)" ::: "memory");
; }
; __global__ void __launch_bounds__(512, 2) fwd(Params P) {
;     ...
;             if (r < I0) { tr_item<1>(INP(4), 2048, 8256, nullptr, wb + OFF_WIN, scr, r, NIN / 32, lane); continue; } r -= I0;
;             if (r < I1) { tr_item<2>(INP(7), 512, 1536, INP(5), wb + OFF_WQ, scr, r, 1536 / 32, lane); continue; } r -= I1;
;             if (r < I2) { tr_item<0>(INP(8), 512, 2048, INP(6), wb + OFF_WKV, scr, r, 2048 / 32, lane); continue; } r -= I2;
;             if (r < I3) { tr_item<0>(INP(9), 1024, 2048, nullptr, wb + OFF_WSBO, scr, r, 2048 / 32, lane); continue; } r -= I3;
;             if (r < I4) { tr_item<0>(INP(10), 1024, 2048, nullptr, wb + OFF_WMLAO, scr, r, 2048 / 32, lane); continue; } r -= I4;
;             if (r < I5) { tr_item<0>(INP(11), 2048, 2048, nullptr, wb + OFF_WOUT, scr, r, 2048 / 32, lane); continue; } r -= I5;
;             if (r < I6) { tr_item<0>(INP(14), 2048, 8192, nullptr, wb + OFF_WUP, scr, r, 8192 / 32, lane); continue; } r -= I6;
;             if (r < I7) { tr_item<0>(INP(15), 8192, 2048, nullptr, wb + OFF_WDOWN, scr, r, 2048 / 32, lane); continue; } r -= I7;
;             if (r < I8) { tr_item<0>(INP(17), 256, 2048, nullptr, wb + OFF_WPLE, scr, r, 2048 / 32, lane); continue; } r -= I8;
.Lp0g_entry:
	v_readfirstlane_b32 s32, v178
	s_load_dwordx2 s[20:21], s[0:1], 0xa8
	v_lshrrev_b32_e32 v0, 5, v179
	v_and_b32_e32 v1, 31, v179
	v_lshrrev_b32_e32 v2, 3, v179
	v_and_b32_e32 v3, 7, v179
	s_lshr_b32 s32, s32, 6
	s_lshl_b32 s32, s32, 14
	v_lshlrev_b32_e32 v1, 2, v1
	v_mul_u32_u24_e32 v4, 0x84, v0
	v_mul_u32_u24_e32 v5, 0x420, v3
	v_add3_u32 v4, v4, v1, s32
	v_lshl_add_u32 v5, v2, 2, v5
	v_add_u32_e32 v5, s32, v5
	v_lshlrev_b32_e32 v3, 4, v3
	s_mov_b32 s4, s50
	s_waitcnt lgkmcnt(0)
	s_add_u32 s20, s20, 0x100000
	s_addc_u32 s21, s21, 0
	s_mov_b32 s16, 0x7580
	s_movk_i32 s15, 0x98
	s_mov_b32 s11, 13
	s_mov_b32 s12, 6
	s_mov_b32 s13, 11
	s_mov_b32 s14, 61603840
	s_cmpk_lt_u32 s4, 0x7580
	s_cselect_b32 s16, 0x7480, s16
	s_cselect_b32 s15, 0x88, s15
	s_cselect_b32 s11, 13, s11
	s_cselect_b32 s12, 6, s12
	s_cselect_b32 s13, 8, s13
	s_cselect_b32 s14, 61079552, s14
	s_cmpk_lt_u32 s4, 0x7480
	s_cselect_b32 s16, 0x5480, s16
	s_cselect_b32 s15, 0x78, s15
	s_cselect_b32 s11, 13, s11
	s_cselect_b32 s12, 6, s12
	s_cselect_b32 s13, 13, s13
	s_cselect_b32 s14, 44302336, s14
	s_cmpk_lt_u32 s4, 0x5480
	s_cselect_b32 s16, 0x3480, s16
	s_cselect_b32 s15, 0x70, s15
	s_cselect_b32 s11, 15, s11
	s_cselect_b32 s12, 8, s12
	s_cselect_b32 s13, 11, s13
	s_cselect_b32 s14, 27525120, s14
	s_cmpk_lt_u32 s4, 0x3480
	s_cselect_b32 s16, 0x2c80, s16
	s_cselect_b32 s15, 0x58, s15
	s_cselect_b32 s11, 13, s11
	s_cselect_b32 s12, 6, s12
	s_cselect_b32 s13, 11, s13
	s_cselect_b32 s14, 23330816, s14
	s_cmpk_lt_u32 s4, 0x2c80
	s_cselect_b32 s16, 0x2880, s16
	s_cselect_b32 s15, 0x50, s15
	s_cselect_b32 s11, 13, s11
	s_cselect_b32 s12, 6, s12
	s_cselect_b32 s13, 10, s13
	s_cselect_b32 s14, 21233664, s14
	s_cmpk_lt_u32 s4, 0x2880
	s_cselect_b32 s16, 0x2480, s16
	s_cselect_b32 s15, 0x48, s15
	s_cselect_b32 s11, 13, s11
	s_cselect_b32 s12, 6, s12
	s_cselect_b32 s13, 10, s13
	s_cselect_b32 s14, 19136512, s14
	s_load_dwordx2 s[6:7], s[0:1], s15
	s_sub_i32 s16, s4, s16
	s_lshl_b32 s19, 1, s12
	s_sub_i32 s19, s19, 1
	s_and_b32 s18, s16, s19
	s_lshr_b32 s17, s16, s12
	s_lshl_b32 s17, s17, 6
	s_lshl_b32 s19, s17, s11
	s_lshl_b32 s29, s18, 7
	s_add_u32 s19, s19, s29
	s_lshl_b32 s10, 2, s11
	v_lshlrev_b32_e32 v6, s11, v0
	v_add_u32_e32 v6, v6, v1
	s_lshl_b32 s29, s18, 5
	s_lshl_b32 s29, s29, s13
	s_add_u32 s29, s29, s17
	s_add_u32 s29, s29, s14
	s_lshl_b32 s29, s29, 1
	s_add_u32 s22, s20, s29
	s_addc_u32 s23, s21, 0
	s_lshl_b32 s24, 16, s13
	s_add_i32 s29, s13, 1
	v_lshlrev_b32_e32 v8, s29, v2
	v_add_u32_e32 v8, v8, v3
	s_waitcnt lgkmcnt(0)
	s_add_u32 s8, s6, s19
	s_addc_u32 s9, s7, 0
	global_load_dword v32, v6, s[8:9] nt
	s_add_u32 s8, s8, s10
	s_addc_u32 s9, s9, 0
	global_load_dword v33, v6, s[8:9] nt
	s_add_u32 s8, s8, s10
	s_addc_u32 s9, s9, 0
	global_load_dword v34, v6, s[8:9] nt
	s_add_u32 s8, s8, s10
	s_addc_u32 s9, s9, 0
	global_load_dword v35, v6, s[8:9] nt
	s_add_u32 s8, s8, s10
	s_addc_u32 s9, s9, 0
	global_load_dword v36, v6, s[8:9] nt
	s_add_u32 s8, s8, s10
	s_addc_u32 s9, s9, 0
	global_load_dword v37, v6, s[8:9] nt
	s_add_u32 s8, s8, s10
	s_addc_u32 s9, s9, 0
	global_load_dword v38, v6, s[8:9] nt
	s_add_u32 s8, s8, s10
	s_addc_u32 s9, s9, 0
	global_load_dword v39, v6, s[8:9] nt
	s_add_u32 s8, s8, s10
	s_addc_u32 s9, s9, 0
	global_load_dword v40, v6, s[8:9] nt
	s_add_u32 s8, s8, s10
	s_addc_u32 s9, s9, 0
	global_load_dword v41, v6, s[8:9] nt
	s_add_u32 s8, s8, s10
	s_addc_u32 s9, s9, 0
	global_load_dword v42, v6, s[8:9] nt
	s_add_u32 s8, s8, s10
	s_addc_u32 s9, s9, 0
	global_load_dword v43, v6, s[8:9] nt
	s_add_u32 s8, s8, s10
	s_addc_u32 s9, s9, 0
	global_load_dword v44, v6, s[8:9] nt
	s_add_u32 s8, s8, s10
	s_addc_u32 s9, s9, 0
	global_load_dword v45, v6, s[8:9] nt
	s_add_u32 s8, s8, s10
	s_addc_u32 s9, s9, 0
	global_load_dword v46, v6, s[8:9] nt
	s_add_u32 s8, s8, s10
	s_addc_u32 s9, s9, 0
	global_load_dword v47, v6, s[8:9] nt
	s_add_u32 s8, s8, s10
	s_addc_u32 s9, s9, 0
	global_load_dword v48, v6, s[8:9] nt
	s_add_u32 s8, s8, s10
	s_addc_u32 s9, s9, 0
	global_load_dword v49, v6, s[8:9] nt
	s_add_u32 s8, s8, s10
	s_addc_u32 s9, s9, 0
	global_load_dword v50, v6, s[8:9] nt
	s_add_u32 s8, s8, s10
	s_addc_u32 s9, s9, 0
	global_load_dword v51, v6, s[8:9] nt
	s_add_u32 s8, s8, s10
	s_addc_u32 s9, s9, 0
	global_load_dword v52, v6, s[8:9] nt
	s_add_u32 s8, s8, s10
	s_addc_u32 s9, s9, 0
	global_load_dword v53, v6, s[8:9] nt
	s_add_u32 s8, s8, s10
	s_addc_u32 s9, s9, 0
	global_load_dword v54, v6, s[8:9] nt
	s_add_u32 s8, s8, s10
	s_addc_u32 s9, s9, 0
	global_load_dword v55, v6, s[8:9] nt
	s_add_u32 s8, s8, s10
	s_addc_u32 s9, s9, 0
	global_load_dword v56, v6, s[8:9] nt
	s_add_u32 s8, s8, s10
	s_addc_u32 s9, s9, 0
	global_load_dword v57, v6, s[8:9] nt
	s_add_u32 s8, s8, s10
	s_addc_u32 s9, s9, 0
	global_load_dword v58, v6, s[8:9] nt
	s_add_u32 s8, s8, s10
	s_addc_u32 s9, s9, 0
	global_load_dword v59, v6, s[8:9] nt
	s_add_u32 s8, s8, s10
	s_addc_u32 s9, s9, 0
	global_load_dword v60, v6, s[8:9] nt
	s_add_u32 s8, s8, s10
	s_addc_u32 s9, s9, 0
	global_load_dword v61, v6, s[8:9] nt
	s_add_u32 s8, s8, s10
	s_addc_u32 s9, s9, 0
	global_load_dword v62, v6, s[8:9] nt
	s_add_u32 s8, s8, s10
	s_addc_u32 s9, s9, 0
	global_load_dword v63, v6, s[8:9] nt
	s_add_i32 s5, s4, s82
	s_cmpk_gt_i32 s5, 0x7d7f
	s_cbranch_scc1 .Lp0g_tail_a
; #define LAS __attribute__((address_space(3)))
; __device__ __forceinline__ unsigned pk2(float lo, float hi) { return pg8::cvt_pk_bf16(lo, hi); }
; template <int KIND> __device__ __forceinline__ void tr_item(const float* __restrict__ W, int K, int Nsrc, const float* __restrict__ gk, bf16_t* WT, LAS float* scr, int item, int nblk, int lane) {
;     const int kb = item / nblk, nb = item - kb * nblk, k0 = 64 * kb, n0 = 32 * nb;
;     const int src = srcmap<KIND>(n0 + (lane & 31));
; #pragma unroll 8
;     for (int i = 0; i < 32; ++i) { const int kk = 2 * i + (lane >> 5); float v = 0.f; if (src >= 0) v = __builtin_nontemporal_load(&W[(size_t)(k0 + kk) * Nsrc + src]); if (gk) v *= gk[k0 + kk]; scr[kk * 33 + (lane & 31)] = v; }
;     asm volatile("s_waitcnt lgkmcnt(0)" ::: "memory");
;     const int c = lane & 7;
; #pragma unroll
;     for (int j = 0; j < 4; ++j) { const int n = (lane >> 3) + 8 * j; const LAS float* s = scr + (8 * c) * 33 + n;
;         u32x4 o; o.x = pk2(s[0 * 33], s[1 * 33]); o.y = pk2(s[2 * 33], s[3 * 33]); o.z = pk2(s[4 * 33], s[5 * 33]); o.w = pk2(s[6 * 33], s[7 * 33]);
;         *(u32x4*)(WT + (size_t)(n0 + n) * K + k0 + 8 * c) = o; }
;     asm volatile("s_waitcnt lgkmcnt(0)" ::: "memory");
; }
	s_mov_b32 s16, 0x7580
	s_movk_i32 s15, 0x98
	s_mov_b32 s11, 13
	s_mov_b32 s12, 6
	s_mov_b32 s13, 11
	s_mov_b32 s14, 61603840
	s_cmpk_lt_u32 s5, 0x7580
	s_cselect_b32 s16, 0x7480, s16
	s_cselect_b32 s15, 0x88, s15
	s_cselect_b32 s11, 13, s11
	s_cselect_b32 s12, 6, s12
	s_cselect_b32 s13, 8, s13
	s_cselect_b32 s14, 61079552, s14
	s_cmpk_lt_u32 s5, 0x7480
	s_cselect_b32 s16, 0x5480, s16
	s_cselect_b32 s15, 0x78, s15
	s_cselect_b32 s11, 13, s11
	s_cselect_b32 s12, 6, s12
	s_cselect_b32 s13, 13, s13
	s_cselect_b32 s14, 44302336, s14
	s_cmpk_lt_u32 s5, 0x5480
	s_cselect_b32 s16, 0x3480, s16
	s_cselect_b32 s15, 0x70, s15
	s_cselect_b32 s11, 15, s11
	s_cselect_b32 s12, 8, s12
	s_cselect_b32 s13, 11, s13
	s_cselect_b32 s14, 27525120, s14
	s_cmpk_lt_u32 s5, 0x3480
	s_cselect_b32 s16, 0x2c80, s16
	s_cselect_b32 s15, 0x58, s15
	s_cselect_b32 s11, 13, s11
	s_cselect_b32 s12, 6, s12
	s_cselect_b32 s13, 11, s13
	s_cselect_b32 s14, 23330816, s14
	s_cmpk_lt_u32 s5, 0x2c80
	s_cselect_b32 s16, 0x2880, s16
	s_cselect_b32 s15, 0x50, s15
	s_cselect_b32 s11, 13, s11
	s_cselect_b32 s12, 6, s12
	s_cselect_b32 s13, 10, s13
	s_cselect_b32 s14, 21233664, s14
	s_cmpk_lt_u32 s5, 0x2880
	s_cselect_b32 s16, 0x2480, s16
	s_cselect_b32 s15, 0x48, s15
	s_cselect_b32 s11, 13, s11
	s_cselect_b32 s12, 6, s12
	s_cselect_b32 s13, 10, s13
	s_cselect_b32 s14, 19136512, s14
	s_load_dwordx2 s[6:7], s[0:1], s15
	s_sub_i32 s16, s5, s16
	s_lshl_b32 s19, 1, s12
	s_sub_i32 s19, s19, 1
	s_and_b32 s18, s16, s19
	s_lshr_b32 s17, s16, s12
	s_lshl_b32 s17, s17, 6
	s_lshl_b32 s19, s17, s11
	s_lshl_b32 s29, s18, 7
	s_add_u32 s19, s19, s29
	s_lshl_b32 s10, 2, s11
	v_lshlrev_b32_e32 v6, s11, v0
	v_add_u32_e32 v6, v6, v1
	s_lshl_b32 s29, s18, 5
	s_lshl_b32 s29, s29, s13
	s_add_u32 s29, s29, s17
	s_add_u32 s29, s29, s14
	s_lshl_b32 s29, s29, 1
	s_add_u32 s26, s20, s29
	s_addc_u32 s27, s21, 0
	s_lshl_b32 s28, 16, s13
	s_add_i32 s29, s13, 1
	v_lshlrev_b32_e32 v9, s29, v2
	v_add_u32_e32 v9, v9, v3
	s_waitcnt lgkmcnt(0)
	s_add_u32 s8, s6, s19
	s_addc_u32 s9, s7, 0
	global_load_dword v64, v6, s[8:9] nt
	s_add_u32 s8, s8, s10
	s_addc_u32 s9, s9, 0
	global_load_dword v65, v6, s[8:9] nt
	s_add_u32 s8, s8, s10
	s_addc_u32 s9, s9, 0
	global_load_dword v66, v6, s[8:9] nt
	s_add_u32 s8, s8, s10
	s_addc_u32 s9, s9, 0
	global_load_dword v67, v6, s[8:9] nt
	s_add_u32 s8, s8, s10
	s_addc_u32 s9, s9, 0
	global_load_dword v68, v6, s[8:9] nt
	s_add_u32 s8, s8, s10
	s_addc_u32 s9, s9, 0
	global_load_dword v69, v6, s[8:9] nt
	s_add_u32 s8, s8, s10
	s_addc_u32 s9, s9, 0
	global_load_dword v70, v6, s[8:9] nt
	s_add_u32 s8, s8, s10
	s_addc_u32 s9, s9, 0
	global_load_dword v71, v6, s[8:9] nt
	s_add_u32 s8, s8, s10
	s_addc_u32 s9, s9, 0
	global_load_dword v72, v6, s[8:9] nt
	s_add_u32 s8, s8, s10
	s_addc_u32 s9, s9, 0
	global_load_dword v73, v6, s[8:9] nt
	s_add_u32 s8, s8, s10
	s_addc_u32 s9, s9, 0
	global_load_dword v74, v6, s[8:9] nt
	s_add_u32 s8, s8, s10
	s_addc_u32 s9, s9, 0
	global_load_dword v75, v6, s[8:9] nt
	s_add_u32 s8, s8, s10
	s_addc_u32 s9, s9, 0
	global_load_dword v76, v6, s[8:9] nt
	s_add_u32 s8, s8, s10
	s_addc_u32 s9, s9, 0
	global_load_dword v77, v6, s[8:9] nt
	s_add_u32 s8, s8, s10
	s_addc_u32 s9, s9, 0
	global_load_dword v78, v6, s[8:9] nt
	s_add_u32 s8, s8, s10
	s_addc_u32 s9, s9, 0
	global_load_dword v79, v6, s[8:9] nt
	s_add_u32 s8, s8, s10
	s_addc_u32 s9, s9, 0
	global_load_dword v80, v6, s[8:9] nt
	s_add_u32 s8, s8, s10
	s_addc_u32 s9, s9, 0
	global_load_dword v81, v6, s[8:9] nt
	s_add_u32 s8, s8, s10
	s_addc_u32 s9, s9, 0
	global_load_dword v82, v6, s[8:9] nt
	s_add_u32 s8, s8, s10
	s_addc_u32 s9, s9, 0
	global_load_dword v83, v6, s[8:9] nt
	s_add_u32 s8, s8, s10
	s_addc_u32 s9, s9, 0
	global_load_dword v84, v6, s[8:9] nt
	s_add_u32 s8, s8, s10
	s_addc_u32 s9, s9, 0
	global_load_dword v85, v6, s[8:9] nt
	s_add_u32 s8, s8, s10
	s_addc_u32 s9, s9, 0
	global_load_dword v86, v6, s[8:9] nt
	s_add_u32 s8, s8, s10
	s_addc_u32 s9, s9, 0
	global_load_dword v87, v6, s[8:9] nt
	s_add_u32 s8, s8, s10
	s_addc_u32 s9, s9, 0
	global_load_dword v88, v6, s[8:9] nt
	s_add_u32 s8, s8, s10
	s_addc_u32 s9, s9, 0
	global_load_dword v89, v6, s[8:9] nt
	s_add_u32 s8, s8, s10
	s_addc_u32 s9, s9, 0
	global_load_dword v90, v6, s[8:9] nt
	s_add_u32 s8, s8, s10
	s_addc_u32 s9, s9, 0
	global_load_dword v91, v6, s[8:9] nt
	s_add_u32 s8, s8, s10
	s_addc_u32 s9, s9, 0
	global_load_dword v92, v6, s[8:9] nt
	s_add_u32 s8, s8, s10
	s_addc_u32 s9, s9, 0
	global_load_dword v93, v6, s[8:9] nt
	s_add_u32 s8, s8, s10
	s_addc_u32 s9, s9, 0
	global_load_dword v94, v6, s[8:9] nt
	s_add_u32 s8, s8, s10
	s_addc_u32 s9, s9, 0
	global_load_dword v95, v6, s[8:9] nt
	s_mov_b64 s[30:31], s[22:23]
	s_waitcnt vmcnt(63)
	ds_write_b32 v4, v32
	s_waitcnt vmcnt(62)
	ds_write_b32 v4, v33 offset:264
	s_waitcnt vmcnt(61)
	ds_write_b32 v4, v34 offset:528
	s_waitcnt vmcnt(60)
	ds_write_b32 v4, v35 offset:792
	s_waitcnt vmcnt(59)
	ds_write_b32 v4, v36 offset:1056
	s_waitcnt vmcnt(58)
	ds_write_b32 v4, v37 offset:1320
	s_waitcnt vmcnt(57)
	ds_write_b32 v4, v38 offset:1584
	s_waitcnt vmcnt(56)
	ds_write_b32 v4, v39 offset:1848
	s_waitcnt vmcnt(55)
	ds_write_b32 v4, v40 offset:2112
	s_waitcnt vmcnt(54)
	ds_write_b32 v4, v41 offset:2376
	s_waitcnt vmcnt(53)
	ds_write_b32 v4, v42 offset:2640
	s_waitcnt vmcnt(52)
	ds_write_b32 v4, v43 offset:2904
	s_waitcnt vmcnt(51)
	ds_write_b32 v4, v44 offset:3168
	s_waitcnt vmcnt(50)
	ds_write_b32 v4, v45 offset:3432
	s_waitcnt vmcnt(49)
	ds_write_b32 v4, v46 offset:3696
	s_waitcnt vmcnt(48)
	ds_write_b32 v4, v47 offset:3960
	s_waitcnt vmcnt(47)
	ds_write_b32 v4, v48 offset:4224
	s_waitcnt vmcnt(46)
; #define LAS __attribute__((address_space(3)))
; __device__ __forceinline__ unsigned pk2(float lo, float hi) { return pg8::cvt_pk_bf16(lo, hi); }
; #define INP(i) ((const float*)(const GAS float*)KARG(8 * (i)))
; template <int KIND> __device__ __forceinline__ void tr_item(const float* __restrict__ W, int K, int Nsrc, const float* __restrict__ gk, bf16_t* WT, LAS float* scr, int item, int nblk, int lane) {
;     ...
;     asm volatile("s_waitcnt lgkmcnt(0)" ::: "memory");
;     const int c = lane & 7;
; #pragma unroll
;     for (int j = 0; j < 4; ++j) { const int n = (lane >> 3) + 8 * j; const LAS float* s = scr + (8 * c) * 33 + n;
;         u32x4 o; o.x = pk2(s[0 * 33], s[1 * 33]); o.y = pk2(s[2 * 33], s[3 * 33]); o.z = pk2(s[4 * 33], s[5 * 33]); o.w = pk2(s[6 * 33], s[7 * 33]);
;         *(u32x4*)(WT + (size_t)(n0 + n) * K + k0 + 8 * c) = o; }
;     asm volatile("s_waitcnt lgkmcnt(0)" ::: "memory");
; }
; __global__ void __launch_bounds__(512, 2) fwd(Params P) {
;     ...
;         for (int it = gw; it < NITEMS; it += NGW) {
;             int r = it;
;             if (r < I0) { tr_item<1>(INP(4), 2048, 8256, nullptr, wb + OFF_WIN, scr, r, NIN / 32, lane); continue; } r -= I0;
;             if (r < I1) { tr_item<2>(INP(7), 512, 1536, INP(5), wb + OFF_WQ, scr, r, 1536 / 32, lane); continue; } r -= I1;
;             if (r < I2) { tr_item<0>(INP(8), 512, 2048, INP(6), wb + OFF_WKV, scr, r, 2048 / 32, lane); continue; } r -= I2;
;             if (r < I3) { tr_item<0>(INP(9), 1024, 2048, nullptr, wb + OFF_WSBO, scr, r, 2048 / 32, lane); continue; } r -= I3;
;             if (r < I4) { tr_item<0>(INP(10), 1024, 2048, nullptr, wb + OFF_WMLAO, scr, r, 2048 / 32, lane); continue; } r -= I4;
;             if (r < I5) { tr_item<0>(INP(11), 2048, 2048, nullptr, wb + OFF_WOUT, scr, r, 2048 / 32, lane); continue; } r -= I5;
;             if (r < I6) { tr_item<0>(INP(14), 2048, 8192, nullptr, wb + OFF_WUP, scr, r, 8192 / 32, lane); continue; } r -= I6;
;             if (r < I7) { tr_item<0>(INP(15), 8192, 2048, nullptr, wb + OFF_WDOWN, scr, r, 2048 / 32, lane); continue; } r -= I7;
;             if (r < I8) { tr_item<0>(INP(17), 256, 2048, nullptr, wb + OFF_WPLE, scr, r, 2048 / 32, lane); continue; } r -= I8;
;             tr_item<0>(INP(19), 2048, 2048, nullptr, wb + OFF_WPG, scr, r, 2048 / 32, lane);
	ds_write_b32 v4, v49 offset:4488
	s_waitcnt vmcnt(45)
	ds_write_b32 v4, v50 offset:4752
	s_waitcnt vmcnt(44)
	ds_write_b32 v4, v51 offset:5016
	s_waitcnt vmcnt(43)
	ds_write_b32 v4, v52 offset:5280
	s_waitcnt vmcnt(42)
	ds_write_b32 v4, v53 offset:5544
	s_waitcnt vmcnt(41)
	ds_write_b32 v4, v54 offset:5808
	s_waitcnt vmcnt(40)
	ds_write_b32 v4, v55 offset:6072
	s_waitcnt vmcnt(39)
	ds_write_b32 v4, v56 offset:6336
	s_waitcnt vmcnt(38)
	ds_write_b32 v4, v57 offset:6600
	s_waitcnt vmcnt(37)
	ds_write_b32 v4, v58 offset:6864
	s_waitcnt vmcnt(36)
	ds_write_b32 v4, v59 offset:7128
	s_waitcnt vmcnt(35)
	ds_write_b32 v4, v60 offset:7392
	s_waitcnt vmcnt(34)
	ds_write_b32 v4, v61 offset:7656
	s_waitcnt vmcnt(33)
	ds_write_b32 v4, v62 offset:7920
	s_waitcnt vmcnt(32)
	ds_write_b32 v4, v63 offset:8184
	s_waitcnt lgkmcnt(0)
	ds_read2_b32 v[96:97], v5 offset0:0 offset1:8
	ds_read2_b32 v[98:99], v5 offset0:16 offset1:24
	ds_read2_b32 v[100:101], v5 offset0:33 offset1:41
	ds_read2_b32 v[102:103], v5 offset0:49 offset1:57
	ds_read2_b32 v[104:105], v5 offset0:66 offset1:74
	ds_read2_b32 v[106:107], v5 offset0:82 offset1:90
	ds_read2_b32 v[108:109], v5 offset0:99 offset1:107
	ds_read2_b32 v[110:111], v5 offset0:115 offset1:123
	ds_read2_b32 v[112:113], v5 offset0:132 offset1:140
	ds_read2_b32 v[114:115], v5 offset0:148 offset1:156
	ds_read2_b32 v[116:117], v5 offset0:165 offset1:173
	ds_read2_b32 v[118:119], v5 offset0:181 offset1:189
	ds_read2_b32 v[120:121], v5 offset0:198 offset1:206
	ds_read2_b32 v[122:123], v5 offset0:214 offset1:222
	ds_read2_b32 v[124:125], v5 offset0:231 offset1:239
	ds_read2_b32 v[126:127], v5 offset0:247 offset1:255
	s_waitcnt lgkmcnt(0)
	v_cvt_pk_bf16_f32 v12, v96, v100
	v_cvt_pk_bf16_f32 v13, v104, v108
	v_cvt_pk_bf16_f32 v14, v112, v116
	v_cvt_pk_bf16_f32 v15, v120, v124
	global_store_dwordx4 v8, v[12:15], s[30:31]
	s_add_u32 s30, s30, s24
	s_addc_u32 s31, s31, 0
	v_cvt_pk_bf16_f32 v16, v97, v101
	v_cvt_pk_bf16_f32 v17, v105, v109
	v_cvt_pk_bf16_f32 v18, v113, v117
	v_cvt_pk_bf16_f32 v19, v121, v125
	global_store_dwordx4 v8, v[16:19], s[30:31]
	s_add_u32 s30, s30, s24
	s_addc_u32 s31, s31, 0
	v_cvt_pk_bf16_f32 v12, v98, v102
	v_cvt_pk_bf16_f32 v13, v106, v110
	v_cvt_pk_bf16_f32 v14, v114, v118
	v_cvt_pk_bf16_f32 v15, v122, v126
	global_store_dwordx4 v8, v[12:15], s[30:31]
	s_add_u32 s30, s30, s24
	s_addc_u32 s31, s31, 0
	v_cvt_pk_bf16_f32 v16, v99, v103
	v_cvt_pk_bf16_f32 v17, v107, v111
	v_cvt_pk_bf16_f32 v18, v115, v119
	v_cvt_pk_bf16_f32 v19, v123, v127
	global_store_dwordx4 v8, v[16:19], s[30:31]
	s_mov_b32 s4, s5
.Lp0g_loop:
	s_add_i32 s5, s4, s82
	s_cmpk_gt_i32 s5, 0x7d7f
	s_cbranch_scc1 .Lp0g_tail_b
	s_mov_b32 s16, 0x7580
	s_movk_i32 s15, 0x98
	s_mov_b32 s11, 13
	s_mov_b32 s12, 6
	s_mov_b32 s13, 11
	s_mov_b32 s14, 61603840
	s_cmpk_lt_u32 s5, 0x7580
	s_cselect_b32 s16, 0x7480, s16
	s_cselect_b32 s15, 0x88, s15
	s_cselect_b32 s11, 13, s11
	s_cselect_b32 s12, 6, s12
	s_cselect_b32 s13, 8, s13
	s_cselect_b32 s14, 61079552, s14
	s_cmpk_lt_u32 s5, 0x7480
	s_cselect_b32 s16, 0x5480, s16
	s_cselect_b32 s15, 0x78, s15
	s_cselect_b32 s11, 13, s11
	s_cselect_b32 s12, 6, s12
	s_cselect_b32 s13, 13, s13
	s_cselect_b32 s14, 44302336, s14
	s_cmpk_lt_u32 s5, 0x5480
	s_cselect_b32 s16, 0x3480, s16
	s_cselect_b32 s15, 0x70, s15
	s_cselect_b32 s11, 15, s11
	s_cselect_b32 s12, 8, s12
	s_cselect_b32 s13, 11, s13
	s_cselect_b32 s14, 27525120, s14
	s_cmpk_lt_u32 s5, 0x3480
	s_cselect_b32 s16, 0x2c80, s16
	s_cselect_b32 s15, 0x58, s15
	s_cselect_b32 s11, 13, s11
	s_cselect_b32 s12, 6, s12
	s_cselect_b32 s13, 11, s13
	s_cselect_b32 s14, 23330816, s14
	s_cmpk_lt_u32 s5, 0x2c80
	s_cselect_b32 s16, 0x2880, s16
	s_cselect_b32 s15, 0x50, s15
	s_cselect_b32 s11, 13, s11
	s_cselect_b32 s12, 6, s12
	s_cselect_b32 s13, 10, s13
	s_cselect_b32 s14, 21233664, s14
	s_cmpk_lt_u32 s5, 0x2880
	s_cselect_b32 s16, 0x2480, s16
	s_cselect_b32 s15, 0x48, s15
	s_cselect_b32 s11, 13, s11
	s_cselect_b32 s12, 6, s12
	s_cselect_b32 s13, 10, s13
	s_cselect_b32 s14, 19136512, s14
	s_load_dwordx2 s[6:7], s[0:1], s15
	s_sub_i32 s16, s5, s16
	s_lshl_b32 s19, 1, s12
	s_sub_i32 s19, s19, 1
	s_and_b32 s18, s16, s19
	s_lshr_b32 s17, s16, s12
	s_lshl_b32 s17, s17, 6
	s_lshl_b32 s19, s17, s11
	s_lshl_b32 s29, s18, 7
	s_add_u32 s19, s19, s29
	s_lshl_b32 s10, 2, s11
	v_lshlrev_b32_e32 v6, s11, v0
	v_add_u32_e32 v6, v6, v1
	s_lshl_b32 s29, s18, 5
	s_lshl_b32 s29, s29, s13
	s_add_u32 s29, s29, s17
	s_add_u32 s29, s29, s14
	s_lshl_b32 s29, s29, 1
	s_add_u32 s22, s20, s29
	s_addc_u32 s23, s21, 0
	s_lshl_b32 s24, 16, s13
	s_add_i32 s29, s13, 1
	v_lshlrev_b32_e32 v8, s29, v2
	v_add_u32_e32 v8, v8, v3
	s_waitcnt lgkmcnt(0)
; #define LAS __attribute__((address_space(3)))
; __device__ __forceinline__ unsigned pk2(float lo, float hi) { return pg8::cvt_pk_bf16(lo, hi); }
; template <int KIND> __device__ __forceinline__ void tr_item(const float* __restrict__ W, int K, int Nsrc, const float* __restrict__ gk, bf16_t* WT, LAS float* scr, int item, int nblk, int lane) {
;     const int kb = item / nblk, nb = item - kb * nblk, k0 = 64 * kb, n0 = 32 * nb;
;     const int src = srcmap<KIND>(n0 + (lane & 31));
; #pragma unroll 8
;     for (int i = 0; i < 32; ++i) { const int kk = 2 * i + (lane >> 5); float v = 0.f; if (src >= 0) v = __builtin_nontemporal_load(&W[(size_t)(k0 + kk) * Nsrc + src]); if (gk) v *= gk[k0 + kk]; scr[kk * 33 + (lane & 31)] = v; }
;     asm volatile("s_waitcnt lgkmcnt(0)" ::: "memory");
;     const int c = lane & 7;
; #pragma unroll
;     for (int j = 0; j < 4; ++j) { const int n = (lane >> 3) + 8 * j; const LAS float* s = scr + (8 * c) * 33 + n;
;         u32x4 o; o.x = pk2(s[0 * 33], s[1 * 33]); o.y = pk2(s[2 * 33], s[3 * 33]); o.z = pk2(s[4 * 33], s[5 * 33]); o.w = pk2(s[6 * 33], s[7 * 33]);
;         *(u32x4*)(WT + (size_t)(n0 + n) * K + k0 + 8 * c) = o; }
;     asm volatile("s_waitcnt lgkmcnt(0)" ::: "memory");
; }
	s_add_u32 s8, s6, s19
	s_addc_u32 s9, s7, 0
	global_load_dword v32, v6, s[8:9] nt
	s_add_u32 s8, s8, s10
	s_addc_u32 s9, s9, 0
	global_load_dword v33, v6, s[8:9] nt
	s_add_u32 s8, s8, s10
	s_addc_u32 s9, s9, 0
	global_load_dword v34, v6, s[8:9] nt
	s_add_u32 s8, s8, s10
	s_addc_u32 s9, s9, 0
	global_load_dword v35, v6, s[8:9] nt
	s_add_u32 s8, s8, s10
	s_addc_u32 s9, s9, 0
	global_load_dword v36, v6, s[8:9] nt
	s_add_u32 s8, s8, s10
	s_addc_u32 s9, s9, 0
	global_load_dword v37, v6, s[8:9] nt
	s_add_u32 s8, s8, s10
	s_addc_u32 s9, s9, 0
	global_load_dword v38, v6, s[8:9] nt
	s_add_u32 s8, s8, s10
	s_addc_u32 s9, s9, 0
	global_load_dword v39, v6, s[8:9] nt
	s_add_u32 s8, s8, s10
	s_addc_u32 s9, s9, 0
	global_load_dword v40, v6, s[8:9] nt
	s_add_u32 s8, s8, s10
	s_addc_u32 s9, s9, 0
	global_load_dword v41, v6, s[8:9] nt
	s_add_u32 s8, s8, s10
	s_addc_u32 s9, s9, 0
	global_load_dword v42, v6, s[8:9] nt
	s_add_u32 s8, s8, s10
	s_addc_u32 s9, s9, 0
	global_load_dword v43, v6, s[8:9] nt
	s_add_u32 s8, s8, s10
	s_addc_u32 s9, s9, 0
	global_load_dword v44, v6, s[8:9] nt
	s_add_u32 s8, s8, s10
	s_addc_u32 s9, s9, 0
	global_load_dword v45, v6, s[8:9] nt
	s_add_u32 s8, s8, s10
	s_addc_u32 s9, s9, 0
	global_load_dword v46, v6, s[8:9] nt
	s_add_u32 s8, s8, s10
	s_addc_u32 s9, s9, 0
	global_load_dword v47, v6, s[8:9] nt
	s_add_u32 s8, s8, s10
	s_addc_u32 s9, s9, 0
	global_load_dword v48, v6, s[8:9] nt
	s_add_u32 s8, s8, s10
	s_addc_u32 s9, s9, 0
	global_load_dword v49, v6, s[8:9] nt
	s_add_u32 s8, s8, s10
	s_addc_u32 s9, s9, 0
	global_load_dword v50, v6, s[8:9] nt
	s_add_u32 s8, s8, s10
	s_addc_u32 s9, s9, 0
	global_load_dword v51, v6, s[8:9] nt
	s_add_u32 s8, s8, s10
	s_addc_u32 s9, s9, 0
	global_load_dword v52, v6, s[8:9] nt
	s_add_u32 s8, s8, s10
	s_addc_u32 s9, s9, 0
	global_load_dword v53, v6, s[8:9] nt
	s_add_u32 s8, s8, s10
	s_addc_u32 s9, s9, 0
	global_load_dword v54, v6, s[8:9] nt
	s_add_u32 s8, s8, s10
	s_addc_u32 s9, s9, 0
	global_load_dword v55, v6, s[8:9] nt
	s_add_u32 s8, s8, s10
	s_addc_u32 s9, s9, 0
	global_load_dword v56, v6, s[8:9] nt
	s_add_u32 s8, s8, s10
	s_addc_u32 s9, s9, 0
	global_load_dword v57, v6, s[8:9] nt
	s_add_u32 s8, s8, s10
	s_addc_u32 s9, s9, 0
	global_load_dword v58, v6, s[8:9] nt
	s_add_u32 s8, s8, s10
	s_addc_u32 s9, s9, 0
	global_load_dword v59, v6, s[8:9] nt
	s_add_u32 s8, s8, s10
	s_addc_u32 s9, s9, 0
	global_load_dword v60, v6, s[8:9] nt
	s_add_u32 s8, s8, s10
	s_addc_u32 s9, s9, 0
	global_load_dword v61, v6, s[8:9] nt
	s_add_u32 s8, s8, s10
	s_addc_u32 s9, s9, 0
	global_load_dword v62, v6, s[8:9] nt
	s_add_u32 s8, s8, s10
	s_addc_u32 s9, s9, 0
	global_load_dword v63, v6, s[8:9] nt
	s_mov_b64 s[30:31], s[26:27]
	s_waitcnt vmcnt(63)
	ds_write_b32 v4, v64
	s_waitcnt vmcnt(63)
	ds_write_b32 v4, v65 offset:264
	s_waitcnt vmcnt(63)
	ds_write_b32 v4, v66 offset:528
	s_waitcnt vmcnt(63)
	ds_write_b32 v4, v67 offset:792
	s_waitcnt vmcnt(63)
	ds_write_b32 v4, v68 offset:1056
	s_waitcnt vmcnt(62)
	ds_write_b32 v4, v69 offset:1320
	s_waitcnt vmcnt(61)
	ds_write_b32 v4, v70 offset:1584
	s_waitcnt vmcnt(60)
	ds_write_b32 v4, v71 offset:1848
	s_waitcnt vmcnt(59)
	ds_write_b32 v4, v72 offset:2112
	s_waitcnt vmcnt(58)
	ds_write_b32 v4, v73 offset:2376
	s_waitcnt vmcnt(57)
	ds_write_b32 v4, v74 offset:2640
	s_waitcnt vmcnt(56)
	ds_write_b32 v4, v75 offset:2904
	s_waitcnt vmcnt(55)
	ds_write_b32 v4, v76 offset:3168
	s_waitcnt vmcnt(54)
	ds_write_b32 v4, v77 offset:3432
	s_waitcnt vmcnt(53)
	ds_write_b32 v4, v78 offset:3696
	s_waitcnt vmcnt(52)
	ds_write_b32 v4, v79 offset:3960
	s_waitcnt vmcnt(51)
	ds_write_b32 v4, v80 offset:4224
	s_waitcnt vmcnt(50)
	ds_write_b32 v4, v81 offset:4488
	s_waitcnt vmcnt(49)
	ds_write_b32 v4, v82 offset:4752
	s_waitcnt vmcnt(48)
	ds_write_b32 v4, v83 offset:5016
	s_waitcnt vmcnt(47)
	ds_write_b32 v4, v84 offset:5280
	s_waitcnt vmcnt(46)
	ds_write_b32 v4, v85 offset:5544
	s_waitcnt vmcnt(45)
	ds_write_b32 v4, v86 offset:5808
	s_waitcnt vmcnt(44)
	ds_write_b32 v4, v87 offset:6072
	s_waitcnt vmcnt(43)
	ds_write_b32 v4, v88 offset:6336
	s_waitcnt vmcnt(42)
	ds_write_b32 v4, v89 offset:6600
	s_waitcnt vmcnt(41)
	ds_write_b32 v4, v90 offset:6864
	s_waitcnt vmcnt(40)
	ds_write_b32 v4, v91 offset:7128
	s_waitcnt vmcnt(39)
	ds_write_b32 v4, v92 offset:7392
	s_waitcnt vmcnt(38)
	ds_write_b32 v4, v93 offset:7656
	s_waitcnt vmcnt(37)
	ds_write_b32 v4, v94 offset:7920
	s_waitcnt vmcnt(36)
	ds_write_b32 v4, v95 offset:8184
	s_waitcnt lgkmcnt(0)
	ds_read2_b32 v[96:97], v5 offset0:0 offset1:8
	ds_read2_b32 v[98:99], v5 offset0:16 offset1:24
	ds_read2_b32 v[100:101], v5 offset0:33 offset1:41
	ds_read2_b32 v[102:103], v5 offset0:49 offset1:57
	ds_read2_b32 v[104:105], v5 offset0:66 offset1:74
	ds_read2_b32 v[106:107], v5 offset0:82 offset1:90
	ds_read2_b32 v[108:109], v5 offset0:99 offset1:107
	ds_read2_b32 v[110:111], v5 offset0:115 offset1:123
	ds_read2_b32 v[112:113], v5 offset0:132 offset1:140
	ds_read2_b32 v[114:115], v5 offset0:148 offset1:156
	ds_read2_b32 v[116:117], v5 offset0:165 offset1:173
	ds_read2_b32 v[118:119], v5 offset0:181 offset1:189
	ds_read2_b32 v[120:121], v5 offset0:198 offset1:206
	ds_read2_b32 v[122:123], v5 offset0:214 offset1:222
	ds_read2_b32 v[124:125], v5 offset0:231 offset1:239
	ds_read2_b32 v[126:127], v5 offset0:247 offset1:255
	s_waitcnt lgkmcnt(0)
	v_cvt_pk_bf16_f32 v12, v96, v100
	v_cvt_pk_bf16_f32 v13, v104, v108
	v_cvt_pk_bf16_f32 v14, v112, v116
	v_cvt_pk_bf16_f32 v15, v120, v124
	global_store_dwordx4 v9, v[12:15], s[30:31]
	s_add_u32 s30, s30, s28
	s_addc_u32 s31, s31, 0
	v_cvt_pk_bf16_f32 v16, v97, v101
	v_cvt_pk_bf16_f32 v17, v105, v109
	v_cvt_pk_bf16_f32 v18, v113, v117
	v_cvt_pk_bf16_f32 v19, v121, v125
	global_store_dwordx4 v9, v[16:19], s[30:31]
	s_add_u32 s30, s30, s28
	s_addc_u32 s31, s31, 0
	v_cvt_pk_bf16_f32 v12, v98, v102
	v_cvt_pk_bf16_f32 v13, v106, v110
	v_cvt_pk_bf16_f32 v14, v114, v118
	v_cvt_pk_bf16_f32 v15, v122, v126
	global_store_dwordx4 v9, v[12:15], s[30:31]
	s_add_u32 s30, s30, s28
	s_addc_u32 s31, s31, 0
	v_cvt_pk_bf16_f32 v16, v99, v103
	v_cvt_pk_bf16_f32 v17, v107, v111
	v_cvt_pk_bf16_f32 v18, v115, v119
	v_cvt_pk_bf16_f32 v19, v123, v127
	global_store_dwordx4 v9, v[16:19], s[30:31]
	s_mov_b32 s4, s5
	s_add_i32 s5, s4, s82
	s_cmpk_gt_i32 s5, 0x7d7f
	s_cbranch_scc1 .Lp0g_tail_a
; #define LAS __attribute__((address_space(3)))
; __device__ __forceinline__ unsigned pk2(float lo, float hi) { return pg8::cvt_pk_bf16(lo, hi); }
; template <int KIND> __device__ __forceinline__ void tr_item(const float* __restrict__ W, int K, int Nsrc, const float* __restrict__ gk, bf16_t* WT, LAS float* scr, int item, int nblk, int lane) {
;     const int kb = item / nblk, nb = item - kb * nblk, k0 = 64 * kb, n0 = 32 * nb;
;     const int src = srcmap<KIND>(n0 + (lane & 31));
; #pragma unroll 8
;     for (int i = 0; i < 32; ++i) { const int kk = 2 * i + (lane >> 5); float v = 0.f; if (src >= 0) v = __builtin_nontemporal_load(&W[(size_t)(k0 + kk) * Nsrc + src]); if (gk) v *= gk[k0 + kk]; scr[kk * 33 + (lane & 31)] = v; }
;     asm volatile("s_waitcnt lgkmcnt(0)" ::: "memory");
;     const int c = lane & 7;
; #pragma unroll
;     for (int j = 0; j < 4; ++j) { const int n = (lane >> 3) + 8 * j; const LAS float* s = scr + (8 * c) * 33 + n;
;         u32x4 o; o.x = pk2(s[0 * 33], s[1 * 33]); o.y = pk2(s[2 * 33], s[3 * 33]); o.z = pk2(s[4 * 33], s[5 * 33]); o.w = pk2(s[6 * 33], s[7 * 33]);
;         *(u32x4*)(WT + (size_t)(n0 + n) * K + k0 + 8 * c) = o; }
;     asm volatile("s_waitcnt lgkmcnt(0)" ::: "memory");
; }
	s_mov_b32 s16, 0x7580
	s_movk_i32 s15, 0x98
	s_mov_b32 s11, 13
	s_mov_b32 s12, 6
	s_mov_b32 s13, 11
	s_mov_b32 s14, 61603840
	s_cmpk_lt_u32 s5, 0x7580
	s_cselect_b32 s16, 0x7480, s16
	s_cselect_b32 s15, 0x88, s15
	s_cselect_b32 s11, 13, s11
	s_cselect_b32 s12, 6, s12
	s_cselect_b32 s13, 8, s13
	s_cselect_b32 s14, 61079552, s14
	s_cmpk_lt_u32 s5, 0x7480
	s_cselect_b32 s16, 0x5480, s16
	s_cselect_b32 s15, 0x78, s15
	s_cselect_b32 s11, 13, s11
	s_cselect_b32 s12, 6, s12
	s_cselect_b32 s13, 13, s13
	s_cselect_b32 s14, 44302336, s14
	s_cmpk_lt_u32 s5, 0x5480
	s_cselect_b32 s16, 0x3480, s16
	s_cselect_b32 s15, 0x70, s15
	s_cselect_b32 s11, 15, s11
	s_cselect_b32 s12, 8, s12
	s_cselect_b32 s13, 11, s13
	s_cselect_b32 s14, 27525120, s14
	s_cmpk_lt_u32 s5, 0x3480
	s_cselect_b32 s16, 0x2c80, s16
	s_cselect_b32 s15, 0x58, s15
	s_cselect_b32 s11, 13, s11
	s_cselect_b32 s12, 6, s12
	s_cselect_b32 s13, 11, s13
	s_cselect_b32 s14, 23330816, s14
	s_cmpk_lt_u32 s5, 0x2c80
	s_cselect_b32 s16, 0x2880, s16
	s_cselect_b32 s15, 0x50, s15
	s_cselect_b32 s11, 13, s11
	s_cselect_b32 s12, 6, s12
	s_cselect_b32 s13, 10, s13
	s_cselect_b32 s14, 21233664, s14
	s_cmpk_lt_u32 s5, 0x2880
	s_cselect_b32 s16, 0x2480, s16
	s_cselect_b32 s15, 0x48, s15
	s_cselect_b32 s11, 13, s11
	s_cselect_b32 s12, 6, s12
	s_cselect_b32 s13, 10, s13
	s_cselect_b32 s14, 19136512, s14
	s_load_dwordx2 s[6:7], s[0:1], s15
	s_sub_i32 s16, s5, s16
	s_lshl_b32 s19, 1, s12
	s_sub_i32 s19, s19, 1
	s_and_b32 s18, s16, s19
	s_lshr_b32 s17, s16, s12
	s_lshl_b32 s17, s17, 6
	s_lshl_b32 s19, s17, s11
	s_lshl_b32 s29, s18, 7
	s_add_u32 s19, s19, s29
	s_lshl_b32 s10, 2, s11
	v_lshlrev_b32_e32 v6, s11, v0
	v_add_u32_e32 v6, v6, v1
	s_lshl_b32 s29, s18, 5
	s_lshl_b32 s29, s29, s13
	s_add_u32 s29, s29, s17
	s_add_u32 s29, s29, s14
	s_lshl_b32 s29, s29, 1
	s_add_u32 s26, s20, s29
	s_addc_u32 s27, s21, 0
	s_lshl_b32 s28, 16, s13
	s_add_i32 s29, s13, 1
	v_lshlrev_b32_e32 v9, s29, v2
	v_add_u32_e32 v9, v9, v3
	s_waitcnt lgkmcnt(0)
	s_add_u32 s8, s6, s19
	s_addc_u32 s9, s7, 0
	global_load_dword v64, v6, s[8:9] nt
	s_add_u32 s8, s8, s10
	s_addc_u32 s9, s9, 0
	global_load_dword v65, v6, s[8:9] nt
	s_add_u32 s8, s8, s10
	s_addc_u32 s9, s9, 0
	global_load_dword v66, v6, s[8:9] nt
	s_add_u32 s8, s8, s10
	s_addc_u32 s9, s9, 0
	global_load_dword v67, v6, s[8:9] nt
	s_add_u32 s8, s8, s10
	s_addc_u32 s9, s9, 0
	global_load_dword v68, v6, s[8:9] nt
	s_add_u32 s8, s8, s10
	s_addc_u32 s9, s9, 0
	global_load_dword v69, v6, s[8:9] nt
	s_add_u32 s8, s8, s10
	s_addc_u32 s9, s9, 0
	global_load_dword v70, v6, s[8:9] nt
	s_add_u32 s8, s8, s10
	s_addc_u32 s9, s9, 0
	global_load_dword v71, v6, s[8:9] nt
	s_add_u32 s8, s8, s10
	s_addc_u32 s9, s9, 0
	global_load_dword v72, v6, s[8:9] nt
	s_add_u32 s8, s8, s10
	s_addc_u32 s9, s9, 0
	global_load_dword v73, v6, s[8:9] nt
	s_add_u32 s8, s8, s10
	s_addc_u32 s9, s9, 0
	global_load_dword v74, v6, s[8:9] nt
	s_add_u32 s8, s8, s10
	s_addc_u32 s9, s9, 0
	global_load_dword v75, v6, s[8:9] nt
	s_add_u32 s8, s8, s10
	s_addc_u32 s9, s9, 0
	global_load_dword v76, v6, s[8:9] nt
	s_add_u32 s8, s8, s10
	s_addc_u32 s9, s9, 0
	global_load_dword v77, v6, s[8:9] nt
	s_add_u32 s8, s8, s10
	s_addc_u32 s9, s9, 0
	global_load_dword v78, v6, s[8:9] nt
	s_add_u32 s8, s8, s10
	s_addc_u32 s9, s9, 0
	global_load_dword v79, v6, s[8:9] nt
	s_add_u32 s8, s8, s10
	s_addc_u32 s9, s9, 0
	global_load_dword v80, v6, s[8:9] nt
	s_add_u32 s8, s8, s10
	s_addc_u32 s9, s9, 0
	global_load_dword v81, v6, s[8:9] nt
	s_add_u32 s8, s8, s10
	s_addc_u32 s9, s9, 0
	global_load_dword v82, v6, s[8:9] nt
	s_add_u32 s8, s8, s10
	s_addc_u32 s9, s9, 0
	global_load_dword v83, v6, s[8:9] nt
	s_add_u32 s8, s8, s10
	s_addc_u32 s9, s9, 0
	global_load_dword v84, v6, s[8:9] nt
	s_add_u32 s8, s8, s10
	s_addc_u32 s9, s9, 0
	global_load_dword v85, v6, s[8:9] nt
	s_add_u32 s8, s8, s10
	s_addc_u32 s9, s9, 0
	global_load_dword v86, v6, s[8:9] nt
	s_add_u32 s8, s8, s10
	s_addc_u32 s9, s9, 0
	global_load_dword v87, v6, s[8:9] nt
	s_add_u32 s8, s8, s10
	s_addc_u32 s9, s9, 0
	global_load_dword v88, v6, s[8:9] nt
	s_add_u32 s8, s8, s10
	s_addc_u32 s9, s9, 0
	global_load_dword v89, v6, s[8:9] nt
	s_add_u32 s8, s8, s10
	s_addc_u32 s9, s9, 0
	global_load_dword v90, v6, s[8:9] nt
	s_add_u32 s8, s8, s10
	s_addc_u32 s9, s9, 0
	global_load_dword v91, v6, s[8:9] nt
	s_add_u32 s8, s8, s10
	s_addc_u32 s9, s9, 0
	global_load_dword v92, v6, s[8:9] nt
	s_add_u32 s8, s8, s10
	s_addc_u32 s9, s9, 0
	global_load_dword v93, v6, s[8:9] nt
	s_add_u32 s8, s8, s10
	s_addc_u32 s9, s9, 0
	global_load_dword v94, v6, s[8:9] nt
	s_add_u32 s8, s8, s10
	s_addc_u32 s9, s9, 0
	global_load_dword v95, v6, s[8:9] nt
	s_mov_b64 s[30:31], s[22:23]
	s_waitcnt vmcnt(63)
	ds_write_b32 v4, v32
	s_waitcnt vmcnt(63)
	ds_write_b32 v4, v33 offset:264
	s_waitcnt vmcnt(63)
	ds_write_b32 v4, v34 offset:528
	s_waitcnt vmcnt(63)
	ds_write_b32 v4, v35 offset:792
	s_waitcnt vmcnt(63)
	ds_write_b32 v4, v36 offset:1056
	s_waitcnt vmcnt(62)
	ds_write_b32 v4, v37 offset:1320
	s_waitcnt vmcnt(61)
	ds_write_b32 v4, v38 offset:1584
	s_waitcnt vmcnt(60)
	ds_write_b32 v4, v39 offset:1848
	s_waitcnt vmcnt(59)
	ds_write_b32 v4, v40 offset:2112
	s_waitcnt vmcnt(58)
	ds_write_b32 v4, v41 offset:2376
	s_waitcnt vmcnt(57)
	ds_write_b32 v4, v42 offset:2640
	s_waitcnt vmcnt(56)
	ds_write_b32 v4, v43 offset:2904
	s_waitcnt vmcnt(55)
	ds_write_b32 v4, v44 offset:3168
	s_waitcnt vmcnt(54)
	ds_write_b32 v4, v45 offset:3432
	s_waitcnt vmcnt(53)
	ds_write_b32 v4, v46 offset:3696
	s_waitcnt vmcnt(52)
	ds_write_b32 v4, v47 offset:3960
	s_waitcnt vmcnt(51)
	ds_write_b32 v4, v48 offset:4224
	s_waitcnt vmcnt(50)
; #define LAS __attribute__((address_space(3)))
; __device__ __forceinline__ unsigned pk2(float lo, float hi) { return pg8::cvt_pk_bf16(lo, hi); }
; template <int KIND> __device__ __forceinline__ void tr_item(const float* __restrict__ W, int K, int Nsrc, const float* __restrict__ gk, bf16_t* WT, LAS float* scr, int item, int nblk, int lane) {
;     ...
;     asm volatile("s_waitcnt lgkmcnt(0)" ::: "memory");
;     const int c = lane & 7;
; #pragma unroll
;     for (int j = 0; j < 4; ++j) { const int n = (lane >> 3) + 8 * j; const LAS float* s = scr + (8 * c) * 33 + n;
;         u32x4 o; o.x = pk2(s[0 * 33], s[1 * 33]); o.y = pk2(s[2 * 33], s[3 * 33]); o.z = pk2(s[4 * 33], s[5 * 33]); o.w = pk2(s[6 * 33], s[7 * 33]);
;         *(u32x4*)(WT + (size_t)(n0 + n) * K + k0 + 8 * c) = o; }
;     asm volatile("s_waitcnt lgkmcnt(0)" ::: "memory");
; }
	ds_write_b32 v4, v49 offset:4488
	s_waitcnt vmcnt(49)
	ds_write_b32 v4, v50 offset:4752
	s_waitcnt vmcnt(48)
	ds_write_b32 v4, v51 offset:5016
	s_waitcnt vmcnt(47)
	ds_write_b32 v4, v52 offset:5280
	s_waitcnt vmcnt(46)
	ds_write_b32 v4, v53 offset:5544
	s_waitcnt vmcnt(45)
	ds_write_b32 v4, v54 offset:5808
	s_waitcnt vmcnt(44)
	ds_write_b32 v4, v55 offset:6072
	s_waitcnt vmcnt(43)
	ds_write_b32 v4, v56 offset:6336
	s_waitcnt vmcnt(42)
	ds_write_b32 v4, v57 offset:6600
	s_waitcnt vmcnt(41)
	ds_write_b32 v4, v58 offset:6864
	s_waitcnt vmcnt(40)
	ds_write_b32 v4, v59 offset:7128
	s_waitcnt vmcnt(39)
	ds_write_b32 v4, v60 offset:7392
	s_waitcnt vmcnt(38)
	ds_write_b32 v4, v61 offset:7656
	s_waitcnt vmcnt(37)
	ds_write_b32 v4, v62 offset:7920
	s_waitcnt vmcnt(36)
	ds_write_b32 v4, v63 offset:8184
	s_waitcnt lgkmcnt(0)
	ds_read2_b32 v[96:97], v5 offset0:0 offset1:8
	ds_read2_b32 v[98:99], v5 offset0:16 offset1:24
	ds_read2_b32 v[100:101], v5 offset0:33 offset1:41
	ds_read2_b32 v[102:103], v5 offset0:49 offset1:57
	ds_read2_b32 v[104:105], v5 offset0:66 offset1:74
	ds_read2_b32 v[106:107], v5 offset0:82 offset1:90
	ds_read2_b32 v[108:109], v5 offset0:99 offset1:107
	ds_read2_b32 v[110:111], v5 offset0:115 offset1:123
	ds_read2_b32 v[112:113], v5 offset0:132 offset1:140
	ds_read2_b32 v[114:115], v5 offset0:148 offset1:156
	ds_read2_b32 v[116:117], v5 offset0:165 offset1:173
	ds_read2_b32 v[118:119], v5 offset0:181 offset1:189
	ds_read2_b32 v[120:121], v5 offset0:198 offset1:206
	ds_read2_b32 v[122:123], v5 offset0:214 offset1:222
	ds_read2_b32 v[124:125], v5 offset0:231 offset1:239
	ds_read2_b32 v[126:127], v5 offset0:247 offset1:255
	s_waitcnt lgkmcnt(0)
	v_cvt_pk_bf16_f32 v12, v96, v100
	v_cvt_pk_bf16_f32 v13, v104, v108
	v_cvt_pk_bf16_f32 v14, v112, v116
	v_cvt_pk_bf16_f32 v15, v120, v124
	global_store_dwordx4 v8, v[12:15], s[30:31]
	s_add_u32 s30, s30, s24
	s_addc_u32 s31, s31, 0
	v_cvt_pk_bf16_f32 v16, v97, v101
	v_cvt_pk_bf16_f32 v17, v105, v109
	v_cvt_pk_bf16_f32 v18, v113, v117
	v_cvt_pk_bf16_f32 v19, v121, v125
	global_store_dwordx4 v8, v[16:19], s[30:31]
	s_add_u32 s30, s30, s24
	s_addc_u32 s31, s31, 0
	v_cvt_pk_bf16_f32 v12, v98, v102
	v_cvt_pk_bf16_f32 v13, v106, v110
	v_cvt_pk_bf16_f32 v14, v114, v118
	v_cvt_pk_bf16_f32 v15, v122, v126
	global_store_dwordx4 v8, v[12:15], s[30:31]
	s_add_u32 s30, s30, s24
	s_addc_u32 s31, s31, 0
	v_cvt_pk_bf16_f32 v16, v99, v103
	v_cvt_pk_bf16_f32 v17, v107, v111
	v_cvt_pk_bf16_f32 v18, v115, v119
	v_cvt_pk_bf16_f32 v19, v123, v127
	global_store_dwordx4 v8, v[16:19], s[30:31]
	s_mov_b32 s4, s5
	s_branch .Lp0g_loop
.Lp0g_tail_a:
	s_mov_b64 s[30:31], s[22:23]
	s_waitcnt vmcnt(0)
	ds_write_b32 v4, v32
	ds_write_b32 v4, v33 offset:264
	ds_write_b32 v4, v34 offset:528
	ds_write_b32 v4, v35 offset:792
	ds_write_b32 v4, v36 offset:1056
	ds_write_b32 v4, v37 offset:1320
	ds_write_b32 v4, v38 offset:1584
	ds_write_b32 v4, v39 offset:1848
	ds_write_b32 v4, v40 offset:2112
	ds_write_b32 v4, v41 offset:2376
	ds_write_b32 v4, v42 offset:2640
	ds_write_b32 v4, v43 offset:2904
	ds_write_b32 v4, v44 offset:3168
	ds_write_b32 v4, v45 offset:3432
	ds_write_b32 v4, v46 offset:3696
	ds_write_b32 v4, v47 offset:3960
	ds_write_b32 v4, v48 offset:4224
	ds_write_b32 v4, v49 offset:4488
	ds_write_b32 v4, v50 offset:4752
	ds_write_b32 v4, v51 offset:5016
	ds_write_b32 v4, v52 offset:5280
	ds_write_b32 v4, v53 offset:5544
	ds_write_b32 v4, v54 offset:5808
	ds_write_b32 v4, v55 offset:6072
	ds_write_b32 v4, v56 offset:6336
	ds_write_b32 v4, v57 offset:6600
	ds_write_b32 v4, v58 offset:6864
	ds_write_b32 v4, v59 offset:7128
	ds_write_b32 v4, v60 offset:7392
	ds_write_b32 v4, v61 offset:7656
	ds_write_b32 v4, v62 offset:7920
	ds_write_b32 v4, v63 offset:8184
	s_waitcnt lgkmcnt(0)
	ds_read2_b32 v[96:97], v5 offset0:0 offset1:8
	ds_read2_b32 v[98:99], v5 offset0:16 offset1:24
	ds_read2_b32 v[100:101], v5 offset0:33 offset1:41
	ds_read2_b32 v[102:103], v5 offset0:49 offset1:57
	ds_read2_b32 v[104:105], v5 offset0:66 offset1:74
	ds_read2_b32 v[106:107], v5 offset0:82 offset1:90
	ds_read2_b32 v[108:109], v5 offset0:99 offset1:107
	ds_read2_b32 v[110:111], v5 offset0:115 offset1:123
	ds_read2_b32 v[112:113], v5 offset0:132 offset1:140
	ds_read2_b32 v[114:115], v5 offset0:148 offset1:156
	ds_read2_b32 v[116:117], v5 offset0:165 offset1:173
	ds_read2_b32 v[118:119], v5 offset0:181 offset1:189
	ds_read2_b32 v[120:121], v5 offset0:198 offset1:206
	ds_read2_b32 v[122:123], v5 offset0:214 offset1:222
	ds_read2_b32 v[124:125], v5 offset0:231 offset1:239
	ds_read2_b32 v[126:127], v5 offset0:247 offset1:255
	s_waitcnt lgkmcnt(0)
	v_cvt_pk_bf16_f32 v12, v96, v100
	v_cvt_pk_bf16_f32 v13, v104, v108
	v_cvt_pk_bf16_f32 v14, v112, v116
	v_cvt_pk_bf16_f32 v15, v120, v124
	global_store_dwordx4 v8, v[12:15], s[30:31]
	s_add_u32 s30, s30, s24
	s_addc_u32 s31, s31, 0
	v_cvt_pk_bf16_f32 v16, v97, v101
	v_cvt_pk_bf16_f32 v17, v105, v109
	v_cvt_pk_bf16_f32 v18, v113, v117
	v_cvt_pk_bf16_f32 v19, v121, v125
	global_store_dwordx4 v8, v[16:19], s[30:31]
	s_add_u32 s30, s30, s24
	s_addc_u32 s31, s31, 0
	v_cvt_pk_bf16_f32 v12, v98, v102
	v_cvt_pk_bf16_f32 v13, v106, v110
	v_cvt_pk_bf16_f32 v14, v114, v118
	v_cvt_pk_bf16_f32 v15, v122, v126
	global_store_dwordx4 v8, v[12:15], s[30:31]
	s_add_u32 s30, s30, s24
	s_addc_u32 s31, s31, 0
	v_cvt_pk_bf16_f32 v16, v99, v103
	v_cvt_pk_bf16_f32 v17, v107, v111
	v_cvt_pk_bf16_f32 v18, v115, v119
	v_cvt_pk_bf16_f32 v19, v123, v127
	global_store_dwordx4 v8, v[16:19], s[30:31]
	s_branch .LBB0_151
; #define LAS __attribute__((address_space(3)))
; __device__ __forceinline__ unsigned pk2(float lo, float hi) { return pg8::cvt_pk_bf16(lo, hi); }
; template <int KIND> __device__ __forceinline__ void tr_item(const float* __restrict__ W, int K, int Nsrc, const float* __restrict__ gk, bf16_t* WT, LAS float* scr, int item, int nblk, int lane) {
;     ...
;     asm volatile("s_waitcnt lgkmcnt(0)" ::: "memory");
;     const int c = lane & 7;
; #pragma unroll
;     for (int j = 0; j < 4; ++j) { const int n = (lane >> 3) + 8 * j; const LAS float* s = scr + (8 * c) * 33 + n;
;         u32x4 o; o.x = pk2(s[0 * 33], s[1 * 33]); o.y = pk2(s[2 * 33], s[3 * 33]); o.z = pk2(s[4 * 33], s[5 * 33]); o.w = pk2(s[6 * 33], s[7 * 33]);
;         *(u32x4*)(WT + (size_t)(n0 + n) * K + k0 + 8 * c) = o; }
;     asm volatile("s_waitcnt lgkmcnt(0)" ::: "memory");
; }
.Lp0g_tail_b:
	s_mov_b64 s[30:31], s[26:27]
	s_waitcnt vmcnt(0)
	ds_write_b32 v4, v64
	ds_write_b32 v4, v65 offset:264
	ds_write_b32 v4, v66 offset:528
	ds_write_b32 v4, v67 offset:792
	ds_write_b32 v4, v68 offset:1056
	ds_write_b32 v4, v69 offset:1320
	ds_write_b32 v4, v70 offset:1584
	ds_write_b32 v4, v71 offset:1848
	ds_write_b32 v4, v72 offset:2112
	ds_write_b32 v4, v73 offset:2376
	ds_write_b32 v4, v74 offset:2640
	ds_write_b32 v4, v75 offset:2904
	ds_write_b32 v4, v76 offset:3168
	ds_write_b32 v4, v77 offset:3432
	ds_write_b32 v4, v78 offset:3696
	ds_write_b32 v4, v79 offset:3960
	ds_write_b32 v4, v80 offset:4224
	ds_write_b32 v4, v81 offset:4488
	ds_write_b32 v4, v82 offset:4752
	ds_write_b32 v4, v83 offset:5016
	ds_write_b32 v4, v84 offset:5280
	ds_write_b32 v4, v85 offset:5544
	ds_write_b32 v4, v86 offset:5808
	ds_write_b32 v4, v87 offset:6072
	ds_write_b32 v4, v88 offset:6336
	ds_write_b32 v4, v89 offset:6600
	ds_write_b32 v4, v90 offset:6864
	ds_write_b32 v4, v91 offset:7128
	ds_write_b32 v4, v92 offset:7392
	ds_write_b32 v4, v93 offset:7656
	ds_write_b32 v4, v94 offset:7920
	ds_write_b32 v4, v95 offset:8184
	s_waitcnt lgkmcnt(0)
	ds_read2_b32 v[96:97], v5 offset0:0 offset1:8
	ds_read2_b32 v[98:99], v5 offset0:16 offset1:24
	ds_read2_b32 v[100:101], v5 offset0:33 offset1:41
	ds_read2_b32 v[102:103], v5 offset0:49 offset1:57
	ds_read2_b32 v[104:105], v5 offset0:66 offset1:74
	ds_read2_b32 v[106:107], v5 offset0:82 offset1:90
	ds_read2_b32 v[108:109], v5 offset0:99 offset1:107
	ds_read2_b32 v[110:111], v5 offset0:115 offset1:123
	ds_read2_b32 v[112:113], v5 offset0:132 offset1:140
	ds_read2_b32 v[114:115], v5 offset0:148 offset1:156
	ds_read2_b32 v[116:117], v5 offset0:165 offset1:173
	ds_read2_b32 v[118:119], v5 offset0:181 offset1:189
	ds_read2_b32 v[120:121], v5 offset0:198 offset1:206
	ds_read2_b32 v[122:123], v5 offset0:214 offset1:222
	ds_read2_b32 v[124:125], v5 offset0:231 offset1:239
	ds_read2_b32 v[126:127], v5 offset0:247 offset1:255
	s_waitcnt lgkmcnt(0)
	v_cvt_pk_bf16_f32 v12, v96, v100
	v_cvt_pk_bf16_f32 v13, v104, v108
	v_cvt_pk_bf16_f32 v14, v112, v116
	v_cvt_pk_bf16_f32 v15, v120, v124
	global_store_dwordx4 v9, v[12:15], s[30:31]
	s_add_u32 s30, s30, s28
	s_addc_u32 s31, s31, 0
	v_cvt_pk_bf16_f32 v16, v97, v101
	v_cvt_pk_bf16_f32 v17, v105, v109
	v_cvt_pk_bf16_f32 v18, v113, v117
	v_cvt_pk_bf16_f32 v19, v121, v125
	global_store_dwordx4 v9, v[16:19], s[30:31]
	s_add_u32 s30, s30, s28
	s_addc_u32 s31, s31, 0
	v_cvt_pk_bf16_f32 v12, v98, v102
	v_cvt_pk_bf16_f32 v13, v106, v110
	v_cvt_pk_bf16_f32 v14, v114, v118
	v_cvt_pk_bf16_f32 v15, v122, v126
	global_store_dwordx4 v9, v[12:15], s[30:31]
	s_add_u32 s30, s30, s28
	s_addc_u32 s31, s31, 0
	v_cvt_pk_bf16_f32 v16, v99, v103
	v_cvt_pk_bf16_f32 v17, v107, v111
	v_cvt_pk_bf16_f32 v18, v115, v119
	v_cvt_pk_bf16_f32 v19, v123, v127
	global_store_dwordx4 v9, v[16:19], s[30:31]
	s_branch .LBB0_151
